# permlane-swap reductions: P3 epilogue row-SSQ and dilated-merge denominators summed across lanes with v_permlane16/32_swap instead of ds_bpermute round trips
# speedup vs baseline: 1.0142x; 1.0142x over previous
.LBB0_279:
	v_mov_b32_e32 v64, v227
	v_mov_b32_e32 v238, v227
	v_lshrrev_b32_e32 v66, 4, v190
	v_subrev_u32_e32 v65, s69, v190
	v_bitop3_b32 v66, v66, 15, v190 bitop3:0x48
	s_add_i32 s78, 0, 0x10000
	v_lshl_add_u32 v74, v65, 7, 0
	v_permlane32_swap_b32_e32 v64, v238
	v_add_f32_e32 v70, v64, v238
	v_lshl_add_u32 v72, v65, 2, s78
	v_xor_b32_e32 v64, v66, v201
	v_xor_b32_e32 v65, v66, v206
	v_xor_b32_e32 v67, v66, v207
	v_xor_b32_e32 v68, v66, v208
	v_xor_b32_e32 v75, v66, v209
	v_xor_b32_e32 v76, v66, v210
	v_xor_b32_e32 v77, v66, v211
	v_xor_b32_e32 v78, v66, v212
	s_and_b64 vcc, exec, s[24:25]
	v_lshl_add_u32 v73, v64, 3, v74
	v_lshl_add_u32 v71, v65, 3, v74
	v_lshl_add_u32 v69, v67, 3, v74
	v_lshl_add_u32 v68, v68, 3, v74
	v_lshl_add_u32 v67, v75, 3, v74
	v_lshl_add_u32 v66, v76, 3, v74
	v_lshl_add_u32 v65, v77, 3, v74
	v_lshl_add_u32 v64, v78, 3, v74
	s_cbranch_vccnz .LBB0_284
	s_mov_b64 s[36:37], -1
	s_and_b64 vcc, exec, s[26:27]
	s_cbranch_vccnz .LBB0_285

.LBB0_289:
	v_mov_b32_e32 v32, v226
	v_mov_b32_e32 v238, v226
	v_lshlrev_b32_e32 v33, s76, v225
	v_add_u32_e32 v33, s77, v33
	v_subrev_u32_e32 v34, s69, v33
	v_lshl_add_u32 v42, v34, 7, 0
	v_permlane32_swap_b32_e32 v32, v238
	v_add_f32_e32 v38, v32, v238
	v_lshrrev_b32_e32 v32, 4, v33
	v_bitop3_b32 v32, v32, 15, v33 bitop3:0x48
	v_lshl_add_u32 v39, v34, 2, s78
	v_xor_b32_e32 v33, v32, v201
	v_xor_b32_e32 v34, v32, v206
	v_xor_b32_e32 v35, v32, v207
	v_xor_b32_e32 v36, v32, v208
	v_xor_b32_e32 v43, v32, v209
	v_xor_b32_e32 v44, v32, v210
	v_xor_b32_e32 v45, v32, v211
	v_xor_b32_e32 v32, v32, v212
	s_andn2_b64 vcc, exec, s[24:25]
	v_lshl_add_u32 v41, v33, 3, v42
	v_lshl_add_u32 v40, v34, 3, v42
	v_lshl_add_u32 v37, v35, 3, v42
	v_lshl_add_u32 v36, v36, 3, v42
	v_lshl_add_u32 v35, v43, 3, v42
	v_lshl_add_u32 v34, v44, 3, v42
	v_lshl_add_u32 v33, v45, 3, v42
	v_lshl_add_u32 v32, v32, 3, v42
	s_cbranch_vccnz .LBB0_291
	ds_read_b64 v[42:43], v41
	ds_read_b32 v52, v39
	ds_read_b64 v[44:45], v40
	ds_read_b64 v[46:47], v37
	s_waitcnt lgkmcnt(3)
	v_lshlrev_b32_e32 v48, 16, v42
	v_and_b32_e32 v49, 0xffff0000, v42
	v_lshlrev_b32_e32 v42, 16, v43
	v_and_b32_e32 v43, 0xffff0000, v43
	v_pk_add_f32 v[18:19], v[18:19], v[42:43]
	s_waitcnt lgkmcnt(1)
	v_lshlrev_b32_e32 v42, 16, v44
	v_and_b32_e32 v43, 0xffff0000, v44
	v_pk_add_f32 v[20:21], v[20:21], v[42:43]
	v_lshlrev_b32_e32 v42, 16, v45
	v_and_b32_e32 v43, 0xffff0000, v45
	ds_read_b64 v[44:45], v36
	v_pk_add_f32 v[22:23], v[22:23], v[42:43]
	s_waitcnt lgkmcnt(1)
	v_lshlrev_b32_e32 v42, 16, v46
	v_and_b32_e32 v43, 0xffff0000, v46
	v_pk_add_f32 v[24:25], v[24:25], v[42:43]
	v_lshlrev_b32_e32 v42, 16, v47
	v_and_b32_e32 v43, 0xffff0000, v47
	v_pk_add_f32 v[16:17], v[16:17], v[48:49]
	v_pk_add_f32 v[26:27], v[26:27], v[42:43]
	ds_read_b64 v[42:43], v35
	ds_read_b64 v[46:47], v34
	ds_read_b64 v[48:49], v33
	s_waitcnt lgkmcnt(3)
	v_lshlrev_b32_e32 v50, 16, v44
	v_and_b32_e32 v51, 0xffff0000, v44
	v_lshlrev_b32_e32 v44, 16, v45
	v_and_b32_e32 v45, 0xffff0000, v45
	v_pk_add_f32 v[30:31], v[30:31], v[44:45]
	s_waitcnt lgkmcnt(2)
	v_lshlrev_b32_e32 v44, 16, v42
	v_and_b32_e32 v45, 0xffff0000, v42
	v_pk_add_f32 v[0:1], v[0:1], v[44:45]
	v_lshlrev_b32_e32 v42, 16, v43
	v_and_b32_e32 v43, 0xffff0000, v43
	ds_read_b64 v[44:45], v32
	v_pk_add_f32 v[2:3], v[2:3], v[42:43]
	s_waitcnt lgkmcnt(2)
	v_lshlrev_b32_e32 v42, 16, v46
	v_and_b32_e32 v43, 0xffff0000, v46
	v_pk_add_f32 v[4:5], v[4:5], v[42:43]
	v_lshlrev_b32_e32 v42, 16, v47
	v_and_b32_e32 v43, 0xffff0000, v47
	v_pk_add_f32 v[6:7], v[6:7], v[42:43]
	s_waitcnt lgkmcnt(1)
	v_lshlrev_b32_e32 v42, 16, v48
	v_and_b32_e32 v43, 0xffff0000, v48
	v_pk_add_f32 v[8:9], v[8:9], v[42:43]
	v_lshlrev_b32_e32 v42, 16, v49
	v_and_b32_e32 v43, 0xffff0000, v49
	v_pk_add_f32 v[10:11], v[10:11], v[42:43]
	s_waitcnt lgkmcnt(0)
	v_lshlrev_b32_e32 v42, 16, v44
	v_and_b32_e32 v43, 0xffff0000, v44
	v_pk_add_f32 v[12:13], v[12:13], v[42:43]
	v_lshlrev_b32_e32 v42, 16, v45
	v_and_b32_e32 v43, 0xffff0000, v45
	v_pk_add_f32 v[28:29], v[28:29], v[50:51]
	v_pk_add_f32 v[14:15], v[14:15], v[42:43]
	v_add_f32_e32 v38, v38, v52

.LBB0_385:
	v_mov_b32_e32 v140, v144
	s_lshl_b32 s9, s44, 8
	v_readfirstlane_b32 s8, v140
	s_bfe_u32 s29, s8, 0x20006
	s_ashr_i32 s8, s8, 2
	s_andn2_b32 s8, s8, 63
	s_add_i32 s8, s8, s9
	v_and_or_b32 v142, v140, 15, s8
	s_lshl_b32 s8, s20, 8
	s_lshl_b32 s9, s29, 6
	v_bfe_u32 v149, v140, 4, 2
	s_or_b32 s8, s9, s8
	v_lshl_or_b32 v140, v149, 3, s8
	v_ashrrev_i32_e32 v143, 31, v142
	v_ashrrev_i32_e32 v141, 31, v140
	v_lshlrev_b64 v[150:151], 10, v[142:143]
	v_lshl_add_u64 v[158:159], v[150:151], 0, v[140:141]
	v_lshl_add_u64 v[160:161], v[158:159], 2, s[12:13]
	v_lshl_add_u64 v[158:159], v[158:159], 1, s[16:17]
	s_lshl_b32 s44, s20, 2
	v_cmp_eq_u32_e32 vcc, 0, v149
	s_ashr_i32 s45, s44, 31
	v_mov_b64_e32 v[152:153], v[126:127]
	v_mov_b64_e32 v[150:151], v[124:125]
	v_mov_b64_e32 v[156:157], v[122:123]
	v_mov_b64_e32 v[154:155], v[120:121]
	v_cvt_pk_bf16_f32 v120, v150, v151
	v_cvt_pk_bf16_f32 v121, v152, v153
	v_cvt_pk_bf16_f32 v122, v154, v155
	v_cvt_pk_bf16_f32 v123, v156, v157
	global_store_dwordx4 v[158:159], v[120:123], off
	s_nop 0
	v_mul_f32_e32 v151, v151, v151
	v_mul_f32_e32 v153, v153, v153
	v_mul_f32_e32 v155, v155, v155
	v_mul_f32_e32 v157, v157, v157
	v_fmac_f32_e32 v151, v150, v150
	v_fmac_f32_e32 v153, v152, v152
	v_fmac_f32_e32 v155, v154, v154
	v_fmac_f32_e32 v157, v156, v156
	v_add_f32_e32 v150, v151, v153
	v_add_f32_e32 v151, v155, v157
	v_add_f32_e32 v150, v150, v151
	v_mov_b64_e32 v[120:121], v[114:115]
	v_mov_b64_e32 v[122:123], v[112:113]
	v_mul_f32_e32 v112, v117, v117
	v_mul_f32_e32 v113, v119, v119
	v_mul_f32_e32 v114, v123, v123
	v_mul_f32_e32 v115, v121, v121
	v_fmac_f32_e32 v112, v116, v116
	v_fmac_f32_e32 v113, v118, v118
	v_fmac_f32_e32 v114, v122, v122
	v_fmac_f32_e32 v115, v120, v120
	v_add_f32_e32 v112, v112, v113
	v_add_f32_e32 v113, v114, v115
	v_add_f32_e32 v112, v112, v113
	v_add_f32_e32 v112, v150, v112
	v_mov_b32_e32 v113, v112
	v_cvt_pk_bf16_f32 v114, v116, v117
	v_cvt_pk_bf16_f32 v115, v118, v119
	v_cvt_pk_bf16_f32 v116, v122, v123
	v_cvt_pk_bf16_f32 v117, v120, v121
	v_permlane16_swap_b32_e32 v113, v112
	v_add_f32_e32 v112, v112, v113
	v_mov_b32_e32 v113, v112
	s_nop 1
	v_permlane32_swap_b32_e32 v113, v112
	global_store_dwordx4 v[158:159], v[114:117], off offset:64
	s_and_saveexec_b64 s[46:47], vcc
	s_cbranch_execz .LBB0_387
	v_lshlrev_b64 v[114:115], 6, v[142:143]
	v_lshl_add_u64 v[114:115], s[6:7], 0, v[114:115]
	v_lshl_add_u64 v[114:115], s[44:45], 2, v[114:115]
	s_lshl_b32 s20, s29, 2
	v_lshl_add_u64 v[114:115], v[114:115], 0, s[20:21]
	s_waitcnt lgkmcnt(0)
	v_add_f32_e32 v112, v112, v113
	global_store_dword v[114:115], v112, off
.LBB0_387:
	s_or_b64 exec, exec, s[46:47]
	v_or_b32_e32 v112, 16, v142
	s_waitcnt lgkmcnt(0)
	v_ashrrev_i32_e32 v113, 31, v112
	v_lshlrev_b64 v[114:115], 10, v[112:113]
	v_lshl_add_u64 v[122:123], v[114:115], 0, v[140:141]
	v_lshl_add_u64 v[124:125], v[122:123], 2, s[12:13]
	v_lshl_add_u64 v[122:123], v[122:123], 1, s[16:17]
	v_mov_b64_e32 v[116:117], v[110:111]
	v_mov_b64_e32 v[114:115], v[108:109]
	v_mov_b64_e32 v[120:121], v[106:107]
	v_mov_b64_e32 v[118:119], v[104:105]
	v_cvt_pk_bf16_f32 v104, v114, v115
	v_cvt_pk_bf16_f32 v105, v116, v117
	v_cvt_pk_bf16_f32 v106, v118, v119
	v_cvt_pk_bf16_f32 v107, v120, v121
	global_store_dwordx4 v[122:123], v[104:107], off
	s_nop 0
	v_mul_f32_e32 v115, v115, v115
	v_mul_f32_e32 v117, v117, v117
	v_mul_f32_e32 v119, v119, v119
	v_mul_f32_e32 v121, v121, v121
	v_fmac_f32_e32 v115, v114, v114
	v_fmac_f32_e32 v117, v116, v116
	v_fmac_f32_e32 v119, v118, v118
	v_fmac_f32_e32 v121, v120, v120
	v_add_f32_e32 v114, v115, v117
	v_add_f32_e32 v115, v119, v121
	v_add_f32_e32 v114, v114, v115
	v_mov_b64_e32 v[104:105], v[98:99]
	v_mov_b64_e32 v[106:107], v[96:97]
	v_mul_f32_e32 v96, v101, v101
	v_mul_f32_e32 v97, v103, v103
	v_mul_f32_e32 v98, v107, v107
	v_mul_f32_e32 v99, v105, v105
	v_fmac_f32_e32 v96, v100, v100
	v_fmac_f32_e32 v97, v102, v102
	v_fmac_f32_e32 v98, v106, v106
	v_fmac_f32_e32 v99, v104, v104
	v_add_f32_e32 v96, v96, v97
	v_add_f32_e32 v97, v98, v99
	v_add_f32_e32 v96, v96, v97
	v_add_f32_e32 v96, v114, v96
	v_mov_b32_e32 v97, v96
	v_cvt_pk_bf16_f32 v98, v100, v101
	v_cvt_pk_bf16_f32 v99, v102, v103
	v_cvt_pk_bf16_f32 v100, v106, v107
	v_cvt_pk_bf16_f32 v101, v104, v105
	v_permlane16_swap_b32_e32 v97, v96
	v_add_f32_e32 v96, v96, v97
	v_mov_b32_e32 v97, v96
	s_nop 1
	v_permlane32_swap_b32_e32 v97, v96
	global_store_dwordx4 v[122:123], v[98:101], off offset:64
	s_and_saveexec_b64 s[46:47], vcc
	s_cbranch_execz .LBB0_389
	v_lshlrev_b64 v[98:99], 6, v[112:113]
	v_lshl_add_u64 v[98:99], s[6:7], 0, v[98:99]
	v_lshl_add_u64 v[98:99], s[44:45], 2, v[98:99]
	s_lshl_b32 s20, s29, 2
	v_lshl_add_u64 v[98:99], v[98:99], 0, s[20:21]
	s_waitcnt lgkmcnt(0)
	v_add_f32_e32 v96, v96, v97
	global_store_dword v[98:99], v96, off
.LBB0_389:
	s_or_b64 exec, exec, s[46:47]
	v_or_b32_e32 v96, 32, v142
	s_waitcnt lgkmcnt(0)
	v_ashrrev_i32_e32 v97, 31, v96
	v_lshlrev_b64 v[98:99], 10, v[96:97]
	v_lshl_add_u64 v[106:107], v[98:99], 0, v[140:141]
	v_lshl_add_u64 v[108:109], v[106:107], 2, s[12:13]
	v_lshl_add_u64 v[106:107], v[106:107], 1, s[16:17]
	v_mov_b64_e32 v[100:101], v[94:95]
	v_mov_b64_e32 v[98:99], v[92:93]
	v_mov_b64_e32 v[104:105], v[90:91]
	v_mov_b64_e32 v[102:103], v[88:89]
	v_cvt_pk_bf16_f32 v88, v98, v99
	v_cvt_pk_bf16_f32 v89, v100, v101
	v_cvt_pk_bf16_f32 v90, v102, v103
	v_cvt_pk_bf16_f32 v91, v104, v105
	global_store_dwordx4 v[106:107], v[88:91], off
	s_nop 0
	v_mul_f32_e32 v99, v99, v99
	v_mul_f32_e32 v101, v101, v101
	v_mul_f32_e32 v103, v103, v103
	v_mul_f32_e32 v105, v105, v105
	v_fmac_f32_e32 v99, v98, v98
	v_fmac_f32_e32 v101, v100, v100
	v_fmac_f32_e32 v103, v102, v102
	v_fmac_f32_e32 v105, v104, v104
	v_add_f32_e32 v98, v99, v101
	v_add_f32_e32 v99, v103, v105
	v_add_f32_e32 v98, v98, v99
	v_mov_b64_e32 v[88:89], v[82:83]
	v_mov_b64_e32 v[90:91], v[80:81]
	v_mul_f32_e32 v80, v85, v85
	v_mul_f32_e32 v81, v87, v87
	v_mul_f32_e32 v82, v91, v91
	v_mul_f32_e32 v83, v89, v89
	v_fmac_f32_e32 v80, v84, v84
	v_fmac_f32_e32 v81, v86, v86
	v_fmac_f32_e32 v82, v90, v90
	v_fmac_f32_e32 v83, v88, v88
	v_add_f32_e32 v80, v80, v81
	v_add_f32_e32 v81, v82, v83
	v_add_f32_e32 v80, v80, v81
	v_add_f32_e32 v80, v98, v80
	v_mov_b32_e32 v81, v80
	v_cvt_pk_bf16_f32 v82, v84, v85
	v_cvt_pk_bf16_f32 v83, v86, v87
	v_cvt_pk_bf16_f32 v84, v90, v91
	v_cvt_pk_bf16_f32 v85, v88, v89
	v_permlane16_swap_b32_e32 v81, v80
	v_add_f32_e32 v80, v80, v81
	v_mov_b32_e32 v81, v80
	s_nop 1
	v_permlane32_swap_b32_e32 v81, v80
	global_store_dwordx4 v[106:107], v[82:85], off offset:64
	s_and_saveexec_b64 s[46:47], vcc
	s_cbranch_execz .LBB0_391
	v_lshlrev_b64 v[82:83], 6, v[96:97]
	v_lshl_add_u64 v[82:83], s[6:7], 0, v[82:83]
	v_lshl_add_u64 v[82:83], s[44:45], 2, v[82:83]
	s_lshl_b32 s20, s29, 2
	v_lshl_add_u64 v[82:83], v[82:83], 0, s[20:21]
	s_waitcnt lgkmcnt(0)
	v_add_f32_e32 v80, v80, v81
	global_store_dword v[82:83], v80, off
.LBB0_391:
	s_or_b64 exec, exec, s[46:47]
	v_or_b32_e32 v80, 48, v142
	s_waitcnt lgkmcnt(0)
	v_ashrrev_i32_e32 v81, 31, v80
	v_lshlrev_b64 v[82:83], 10, v[80:81]
	v_lshl_add_u64 v[90:91], v[82:83], 0, v[140:141]
	v_lshl_add_u64 v[92:93], v[90:91], 2, s[12:13]
	v_lshl_add_u64 v[90:91], v[90:91], 1, s[16:17]
	v_mov_b64_e32 v[84:85], v[78:79]
	v_mov_b64_e32 v[82:83], v[76:77]
	v_mov_b64_e32 v[88:89], v[74:75]
	v_mov_b64_e32 v[86:87], v[72:73]
	v_cvt_pk_bf16_f32 v72, v82, v83
	v_cvt_pk_bf16_f32 v73, v84, v85
	v_cvt_pk_bf16_f32 v74, v86, v87
	v_cvt_pk_bf16_f32 v75, v88, v89
	global_store_dwordx4 v[90:91], v[72:75], off
	s_nop 0
	v_mul_f32_e32 v83, v83, v83
	v_mul_f32_e32 v85, v85, v85
	v_mul_f32_e32 v87, v87, v87
	v_mul_f32_e32 v89, v89, v89
	v_fmac_f32_e32 v83, v82, v82
	v_fmac_f32_e32 v85, v84, v84
	v_fmac_f32_e32 v87, v86, v86
	v_fmac_f32_e32 v89, v88, v88
	v_add_f32_e32 v82, v83, v85
	v_add_f32_e32 v83, v87, v89
	v_add_f32_e32 v82, v82, v83
	v_mov_b64_e32 v[72:73], v[66:67]
	v_mov_b64_e32 v[74:75], v[64:65]
	v_mul_f32_e32 v64, v69, v69
	v_mul_f32_e32 v65, v71, v71
	v_mul_f32_e32 v66, v75, v75
	v_mul_f32_e32 v67, v73, v73
	v_fmac_f32_e32 v64, v68, v68
	v_fmac_f32_e32 v65, v70, v70
	v_fmac_f32_e32 v66, v74, v74
	v_fmac_f32_e32 v67, v72, v72
	v_add_f32_e32 v64, v64, v65
	v_add_f32_e32 v65, v66, v67
	v_add_f32_e32 v64, v64, v65
	v_add_f32_e32 v64, v82, v64
	v_mov_b32_e32 v65, v64
	v_cvt_pk_bf16_f32 v66, v68, v69
	v_cvt_pk_bf16_f32 v67, v70, v71
	v_cvt_pk_bf16_f32 v68, v74, v75
	v_cvt_pk_bf16_f32 v69, v72, v73
	v_permlane16_swap_b32_e32 v65, v64
	v_add_f32_e32 v64, v64, v65
	v_mov_b32_e32 v65, v64
	s_nop 1
	v_permlane32_swap_b32_e32 v65, v64
	global_store_dwordx4 v[90:91], v[66:69], off offset:64
	s_and_saveexec_b64 s[46:47], vcc
	s_cbranch_execz .LBB0_393
	v_lshlrev_b64 v[66:67], 6, v[80:81]
	v_lshl_add_u64 v[66:67], s[6:7], 0, v[66:67]
	v_lshl_add_u64 v[66:67], s[44:45], 2, v[66:67]
	s_lshl_b32 s20, s29, 2
	v_lshl_add_u64 v[66:67], v[66:67], 0, s[20:21]
	s_waitcnt lgkmcnt(0)
	v_add_f32_e32 v64, v64, v65
	global_store_dword v[66:67], v64, off
.LBB0_393:
	s_or_b64 exec, exec, s[46:47]
	v_add_u32_e32 v64, 0x80, v142
	s_waitcnt lgkmcnt(0)
	v_ashrrev_i32_e32 v65, 31, v64
	v_lshlrev_b64 v[66:67], 10, v[64:65]
	v_lshl_add_u64 v[74:75], v[66:67], 0, v[140:141]
	v_lshl_add_u64 v[76:77], v[74:75], 2, s[12:13]
	v_lshl_add_u64 v[74:75], v[74:75], 1, s[16:17]
	v_mov_b64_e32 v[68:69], v[62:63]
	v_mov_b64_e32 v[66:67], v[60:61]
	v_mov_b64_e32 v[72:73], v[58:59]
	v_mov_b64_e32 v[70:71], v[56:57]
	v_cvt_pk_bf16_f32 v56, v66, v67
	v_cvt_pk_bf16_f32 v57, v68, v69
	v_cvt_pk_bf16_f32 v58, v70, v71
	v_cvt_pk_bf16_f32 v59, v72, v73
	global_store_dwordx4 v[74:75], v[56:59], off
	s_nop 0
	v_mul_f32_e32 v67, v67, v67
	v_mul_f32_e32 v69, v69, v69
	v_mul_f32_e32 v71, v71, v71
	v_mul_f32_e32 v73, v73, v73
	v_fmac_f32_e32 v67, v66, v66
	v_fmac_f32_e32 v69, v68, v68
	v_fmac_f32_e32 v71, v70, v70
	v_fmac_f32_e32 v73, v72, v72
	v_add_f32_e32 v66, v67, v69
	v_add_f32_e32 v67, v71, v73
	v_add_f32_e32 v66, v66, v67
	v_mov_b64_e32 v[56:57], v[50:51]
	v_mov_b64_e32 v[58:59], v[48:49]
	v_mul_f32_e32 v48, v53, v53
	v_mul_f32_e32 v49, v55, v55
	v_mul_f32_e32 v50, v59, v59
	v_mul_f32_e32 v51, v57, v57
	v_fmac_f32_e32 v48, v52, v52
	v_fmac_f32_e32 v49, v54, v54
	v_fmac_f32_e32 v50, v58, v58
	v_fmac_f32_e32 v51, v56, v56
	v_add_f32_e32 v48, v48, v49
	v_add_f32_e32 v49, v50, v51
	v_add_f32_e32 v48, v48, v49
	v_add_f32_e32 v48, v66, v48
	v_mov_b32_e32 v49, v48
	v_cvt_pk_bf16_f32 v50, v52, v53
	v_cvt_pk_bf16_f32 v51, v54, v55
	v_cvt_pk_bf16_f32 v52, v58, v59
	v_cvt_pk_bf16_f32 v53, v56, v57
	v_permlane16_swap_b32_e32 v49, v48
	v_add_f32_e32 v48, v48, v49
	v_mov_b32_e32 v49, v48
	s_nop 1
	v_permlane32_swap_b32_e32 v49, v48
	global_store_dwordx4 v[74:75], v[50:53], off offset:64
	s_and_saveexec_b64 s[46:47], vcc
	s_cbranch_execz .LBB0_395
	v_lshlrev_b64 v[50:51], 6, v[64:65]
	v_lshl_add_u64 v[50:51], s[6:7], 0, v[50:51]
	v_lshl_add_u64 v[50:51], s[44:45], 2, v[50:51]
	s_lshl_b32 s20, s29, 2
	v_lshl_add_u64 v[50:51], v[50:51], 0, s[20:21]
	s_waitcnt lgkmcnt(0)
	v_add_f32_e32 v48, v48, v49
	global_store_dword v[50:51], v48, off
.LBB0_395:
	s_or_b64 exec, exec, s[46:47]
	v_add_u32_e32 v48, 0x90, v142
	s_waitcnt lgkmcnt(0)
	v_ashrrev_i32_e32 v49, 31, v48
	v_lshlrev_b64 v[50:51], 10, v[48:49]
	v_lshl_add_u64 v[58:59], v[50:51], 0, v[140:141]
	v_lshl_add_u64 v[60:61], v[58:59], 2, s[12:13]
	v_lshl_add_u64 v[58:59], v[58:59], 1, s[16:17]
	v_mov_b64_e32 v[52:53], v[46:47]
	v_mov_b64_e32 v[50:51], v[44:45]
	v_mov_b64_e32 v[56:57], v[42:43]
	v_mov_b64_e32 v[54:55], v[40:41]
	v_cvt_pk_bf16_f32 v40, v50, v51
	v_cvt_pk_bf16_f32 v41, v52, v53
	v_cvt_pk_bf16_f32 v42, v54, v55
	v_cvt_pk_bf16_f32 v43, v56, v57
	global_store_dwordx4 v[58:59], v[40:43], off
	s_nop 0
	v_mul_f32_e32 v51, v51, v51
	v_mul_f32_e32 v53, v53, v53
	v_mul_f32_e32 v55, v55, v55
	v_mul_f32_e32 v57, v57, v57
	v_fmac_f32_e32 v51, v50, v50
	v_fmac_f32_e32 v53, v52, v52
	v_fmac_f32_e32 v55, v54, v54
	v_fmac_f32_e32 v57, v56, v56
	v_add_f32_e32 v50, v51, v53
	v_add_f32_e32 v51, v55, v57
	v_add_f32_e32 v50, v50, v51
	v_mov_b64_e32 v[40:41], v[34:35]
	v_mov_b64_e32 v[42:43], v[32:33]
	v_mul_f32_e32 v32, v37, v37
	v_mul_f32_e32 v33, v39, v39
	v_mul_f32_e32 v34, v43, v43
	v_mul_f32_e32 v35, v41, v41
	v_fmac_f32_e32 v32, v36, v36
	v_fmac_f32_e32 v33, v38, v38
	v_fmac_f32_e32 v34, v42, v42
	v_fmac_f32_e32 v35, v40, v40
	v_add_f32_e32 v32, v32, v33
	v_add_f32_e32 v33, v34, v35
	v_add_f32_e32 v32, v32, v33
	v_add_f32_e32 v32, v50, v32
	v_mov_b32_e32 v33, v32
	v_cvt_pk_bf16_f32 v34, v36, v37
	v_cvt_pk_bf16_f32 v35, v38, v39
	v_cvt_pk_bf16_f32 v36, v42, v43
	v_cvt_pk_bf16_f32 v37, v40, v41
	v_permlane16_swap_b32_e32 v33, v32
	v_add_f32_e32 v32, v32, v33
	v_mov_b32_e32 v33, v32
	s_nop 1
	v_permlane32_swap_b32_e32 v33, v32
	global_store_dwordx4 v[58:59], v[34:37], off offset:64
	s_and_saveexec_b64 s[46:47], vcc
	s_cbranch_execz .LBB0_397
	v_lshlrev_b64 v[34:35], 6, v[48:49]
	v_lshl_add_u64 v[34:35], s[6:7], 0, v[34:35]
	v_lshl_add_u64 v[34:35], s[44:45], 2, v[34:35]
	s_lshl_b32 s20, s29, 2
	v_lshl_add_u64 v[34:35], v[34:35], 0, s[20:21]
	s_waitcnt lgkmcnt(0)
	v_add_f32_e32 v32, v32, v33
	global_store_dword v[34:35], v32, off
.LBB0_397:
	s_or_b64 exec, exec, s[46:47]
	v_add_u32_e32 v32, 0xa0, v142
	s_waitcnt lgkmcnt(0)
	v_ashrrev_i32_e32 v33, 31, v32
	v_lshlrev_b64 v[34:35], 10, v[32:33]
	v_lshl_add_u64 v[42:43], v[34:35], 0, v[140:141]
	v_lshl_add_u64 v[44:45], v[42:43], 2, s[12:13]
	v_lshl_add_u64 v[42:43], v[42:43], 1, s[16:17]
	v_mov_b64_e32 v[36:37], v[30:31]
	v_mov_b64_e32 v[34:35], v[28:29]
	v_mov_b64_e32 v[40:41], v[26:27]
	v_mov_b64_e32 v[38:39], v[24:25]
	v_cvt_pk_bf16_f32 v24, v34, v35
	v_cvt_pk_bf16_f32 v25, v36, v37
	v_cvt_pk_bf16_f32 v26, v38, v39
	v_cvt_pk_bf16_f32 v27, v40, v41
	global_store_dwordx4 v[42:43], v[24:27], off
	s_nop 0
	v_mul_f32_e32 v35, v35, v35
	v_mul_f32_e32 v37, v37, v37
	v_mul_f32_e32 v39, v39, v39
	v_mul_f32_e32 v41, v41, v41
	v_fmac_f32_e32 v35, v34, v34
	v_fmac_f32_e32 v37, v36, v36
	v_fmac_f32_e32 v39, v38, v38
	v_fmac_f32_e32 v41, v40, v40
	v_add_f32_e32 v34, v35, v37
	v_add_f32_e32 v35, v39, v41
	v_add_f32_e32 v34, v34, v35
	v_mov_b64_e32 v[24:25], v[18:19]
	v_mov_b64_e32 v[26:27], v[16:17]
	v_mul_f32_e32 v16, v21, v21
	v_mul_f32_e32 v17, v23, v23
	v_mul_f32_e32 v18, v27, v27
	v_mul_f32_e32 v19, v25, v25
	v_fmac_f32_e32 v16, v20, v20
	v_fmac_f32_e32 v17, v22, v22
	v_fmac_f32_e32 v18, v26, v26
	v_fmac_f32_e32 v19, v24, v24
	v_add_f32_e32 v16, v16, v17
	v_add_f32_e32 v17, v18, v19
	v_add_f32_e32 v16, v16, v17
	v_add_f32_e32 v16, v34, v16
	v_mov_b32_e32 v17, v16
	v_cvt_pk_bf16_f32 v18, v20, v21
	v_cvt_pk_bf16_f32 v19, v22, v23
	v_cvt_pk_bf16_f32 v20, v26, v27
	v_cvt_pk_bf16_f32 v21, v24, v25
	v_permlane16_swap_b32_e32 v17, v16
	v_add_f32_e32 v16, v16, v17
	v_mov_b32_e32 v17, v16
	s_nop 1
	v_permlane32_swap_b32_e32 v17, v16
	global_store_dwordx4 v[42:43], v[18:21], off offset:64
	s_and_saveexec_b64 s[46:47], vcc
	s_cbranch_execz .LBB0_399
	v_lshlrev_b64 v[18:19], 6, v[32:33]
	v_lshl_add_u64 v[18:19], s[6:7], 0, v[18:19]
	v_lshl_add_u64 v[18:19], s[44:45], 2, v[18:19]
	s_lshl_b32 s20, s29, 2
	v_lshl_add_u64 v[18:19], v[18:19], 0, s[20:21]
	s_waitcnt lgkmcnt(0)
	v_add_f32_e32 v16, v16, v17
	global_store_dword v[18:19], v16, off
.LBB0_399:
	s_or_b64 exec, exec, s[46:47]
	v_add_u32_e32 v16, 0xb0, v142
	s_waitcnt lgkmcnt(0)
	v_ashrrev_i32_e32 v17, 31, v16
	v_lshlrev_b64 v[18:19], 10, v[16:17]
	v_lshl_add_u64 v[26:27], v[18:19], 0, v[140:141]
	v_lshl_add_u64 v[28:29], v[26:27], 2, s[12:13]
	v_lshl_add_u64 v[26:27], v[26:27], 1, s[16:17]
	v_mov_b64_e32 v[20:21], v[14:15]
	v_mov_b64_e32 v[18:19], v[12:13]
	v_mov_b64_e32 v[24:25], v[10:11]
	v_mov_b64_e32 v[22:23], v[8:9]
	v_cvt_pk_bf16_f32 v8, v18, v19
	v_cvt_pk_bf16_f32 v9, v20, v21
	v_cvt_pk_bf16_f32 v10, v22, v23
	v_cvt_pk_bf16_f32 v11, v24, v25
	global_store_dwordx4 v[26:27], v[8:11], off
	s_nop 0
	v_mul_f32_e32 v19, v19, v19
	v_mul_f32_e32 v21, v21, v21
	v_mul_f32_e32 v23, v23, v23
	v_mul_f32_e32 v25, v25, v25
	v_fmac_f32_e32 v19, v18, v18
	v_fmac_f32_e32 v21, v20, v20
	v_fmac_f32_e32 v23, v22, v22
	v_fmac_f32_e32 v25, v24, v24
	v_add_f32_e32 v18, v19, v21
	v_add_f32_e32 v19, v23, v25
	v_add_f32_e32 v18, v18, v19
	v_mov_b64_e32 v[8:9], v[2:3]
	v_mov_b64_e32 v[10:11], v[0:1]
	v_mul_f32_e32 v0, v5, v5
	v_mul_f32_e32 v1, v7, v7
	v_mul_f32_e32 v2, v11, v11
	v_mul_f32_e32 v3, v9, v9
	v_fmac_f32_e32 v0, v4, v4
	v_fmac_f32_e32 v1, v6, v6
	v_fmac_f32_e32 v2, v10, v10
	v_fmac_f32_e32 v3, v8, v8
	v_add_f32_e32 v0, v0, v1
	v_add_f32_e32 v1, v2, v3
	v_add_f32_e32 v0, v0, v1
	v_add_f32_e32 v0, v18, v0
	v_mov_b32_e32 v1, v0
	v_cvt_pk_bf16_f32 v2, v4, v5
	v_cvt_pk_bf16_f32 v3, v6, v7
	v_cvt_pk_bf16_f32 v4, v10, v11
	v_cvt_pk_bf16_f32 v5, v8, v9
	v_permlane16_swap_b32_e32 v1, v0
	v_add_f32_e32 v0, v0, v1
	v_mov_b32_e32 v1, v0
	s_nop 1
	v_permlane32_swap_b32_e32 v1, v0
	global_store_dwordx4 v[26:27], v[2:5], off offset:64
	s_and_saveexec_b64 s[46:47], vcc
	s_cbranch_execz .LBB0_401
	v_lshlrev_b64 v[2:3], 6, v[16:17]
	v_lshl_add_u64 v[2:3], s[6:7], 0, v[2:3]
	v_lshl_add_u64 v[2:3], s[44:45], 2, v[2:3]
	s_lshl_b32 s20, s29, 2
	v_lshl_add_u64 v[2:3], v[2:3], 0, s[20:21]
	s_waitcnt lgkmcnt(0)
	v_add_f32_e32 v0, v0, v1
	global_store_dword v[2:3], v0, off
